# team stagger widened: teams 4-7 start P1 ~8us late instead of ~4us
# speedup vs baseline: 1.0005x; 1.0005x over previous
.LBB0_165:
	s_or_b64 exec, exec, s[0:1]
	s_lshr_b32 s97, s75, 2
	s_mul_i32 s97, s97, 8
